# v24 + NSA in-projection weight copy moved out of the prologue into layer 0's gate/up tail slot (hand-written pipelined item loop, masked last column block)
# baseline (speedup 1.0000x reference)
.LBB0_84:
	s_sub_i32 s5, s12, s5
	s_cmpk_lt_i32 s5, 0x8000
	s_cbranch_scc1 .LBB0_449
	v_lshrrev_b32_e32 v2, 3, v1
	v_and_b32_e32 v90, 60, v78
	v_lshlrev_b32_e32 v89, 1, v77
	v_mul_u32_u24_e32 v98, 0x104, v77
	v_mul_u32_u24_e32 v99, 0x410, v76
	v_lshlrev_b32_e32 v66, 3, v76
	v_mov_b32_e32 v67, 0
	v_or_b32_e32 v91, 8, v2
	v_or_b32_e32 v92, 16, v2
	v_or_b32_e32 v93, 24, v2
	v_or_b32_e32 v94, 32, v2
	v_or_b32_e32 v95, 40, v2
	v_or_b32_e32 v96, 48, v2
	v_or_b32_e32 v97, 56, v2
	s_cbranch_execz .LBB0_450
	v_mov_b32_e32 v88, v2
.LBB0_87:
	v_lshlrev_b32_e32 v2, 2, v90
	v_add3_u32 v78, s10, v2, v98
	v_add_u32_e32 v2, s10, v99
	v_lshl_add_u64 v[70:71], v[66:67], 1, s[2:3]
	s_mov_b64 s[0:1], 0x100000
	s_addk_i32 s5, 0
	v_lshl_add_u64 v[66:67], v[70:71], 0, s[0:1]
	v_lshl_add_u32 v79, v88, 2, v2
	v_lshl_add_u32 v80, v91, 2, v2
	v_lshl_add_u32 v81, v92, 2, v2
	v_lshl_add_u32 v82, v93, 2, v2
	v_lshl_add_u32 v83, v94, 2, v2
	v_lshl_add_u32 v84, v95, 2, v2
	v_lshl_add_u32 v85, v96, 2, v2
	v_lshl_add_u32 v86, v97, 2, v2
	s_mov_b32 s1, 0
	s_movk_i32 s12, 0x400
	s_mov_b32 s13, 0
	s_branch .LBB0_89

.Ltrn_entry:
	s_cmp_lg_u32 s44, 0
	s_cbranch_scc1 .LBB0_2224
	v_readlane_b32 s8, v251, 48
	v_readlane_b32 s9, v251, 54
	v_readlane_b32 s34, v251, 32
	v_readlane_b32 s35, v251, 33
	v_readlane_b32 s36, v251, 20
	v_readlane_b32 s37, v251, 21
	v_readlane_b32 s6, v251, 2
	v_readlane_b32 s7, v251, 3
	s_nop 0
	s_sub_i32 s8, s8, 128
	s_lshl_b32 s8, s8, 3
	s_lshr_b32 s9, s9, 6
	s_add_i32 s8, s8, s9
	s_mul_i32 s32, s9, 0x2100
	s_add_u32 s36, s36, 0x8000
	s_addc_u32 s37, s37, 0
	s_add_u32 s6, s6, 0x900000
	s_addc_u32 s7, s7, 0
	v_mbcnt_lo_u32_b32 v32, -1, 0
	v_mbcnt_hi_u32_b32 v32, -1, v32
	v_lshrrev_b32_e32 v34, 4, v32
	v_and_b32_e32 v35, 15, v32
	v_and_b32_e32 v36, 7, v32
	v_lshrrev_b32_e32 v37, 3, v32
	v_lshlrev_b32_e32 v30, 3, v34
	v_mul_u32_u24_e32 v38, 0xe300, v34
	v_lshl_add_u32 v38, v35, 4, v38
	v_mov_b32_e32 v0, v38
	v_add_u32_e32 v1, 0x7180, v38
	v_add_u32_e32 v2, 0x38c00, v38
	v_add_u32_e32 v3, 0x3fd80, v38
	v_add_u32_e32 v4, 0x71800, v38
	v_add_u32_e32 v5, 0x78980, v38
	v_add_u32_e32 v6, 0xaa400, v38
	v_add_u32_e32 v7, 0xb1580, v38
	v_add_u32_e32 v8, 0xe3000, v38
	v_add_u32_e32 v9, 0xea180, v38
	v_add_u32_e32 v10, 0x11bc00, v38
	v_add_u32_e32 v11, 0x122d80, v38
	v_add_u32_e32 v16, 0x154800, v38
	v_add_u32_e32 v17, 0x15b980, v38
	v_add_u32_e32 v18, 0x18d400, v38
	v_add_u32_e32 v19, 0x194580, v38
	v_lshlrev_b32_e32 v39, 13, v37
	v_lshl_add_u32 v39, v36, 4, v39
	v_mov_b32_e32 v20, v39
	v_add_u32_e32 v21, 0x10000, v39
	v_add_u32_e32 v22, 0x20000, v39
	v_add_u32_e32 v23, 0x30000, v39
	v_add_u32_e32 v24, 0x40000, v39
	v_add_u32_e32 v25, 0x50000, v39
	v_add_u32_e32 v26, 0x60000, v39
	v_add_u32_e32 v27, 0x70000, v39
	v_mul_u32_u24_e32 v28, 0x104, v34
	v_lshl_add_u32 v28, v35, 4, v28
	v_add_u32_e32 v28, s32, v28
	v_mul_u32_u24_e32 v29, 0x410, v36
	v_lshl_add_u32 v29, v37, 2, v29
	v_add_u32_e32 v29, s32, v29
	s_cmpk_lt_i32 s8, 0x1c80
	s_cbranch_scc0 .Ltrn_done
	s_mul_i32 s23, s8, 0x8fb9
	s_lshr_b32 s23, s23, 22
	s_mul_i32 s25, s23, 0x72
	s_sub_i32 s24, s8, s25
	s_mul_i32 s25, s23, 0x1c6000
	s_lshl_b32 s33, s24, 8
	s_add_i32 s25, s25, s33
	s_add_u32 s26, s34, s25
	s_addc_u32 s27, s35, 0
	s_lshl_b32 s25, s23, 8
	s_add_u32 s28, s36, s25
	s_addc_u32 s29, s37, 0
	s_cmpk_lg_u32 s24, 0x71
	s_cbranch_scc1 .Ltrn_ldfull1
	s_mov_b32 exec_lo, 0x00ff00ff
	s_mov_b32 exec_hi, 0x00ff00ff
.Ltrn_ldfull1:
	global_load_dwordx4 v[44:47], v0, s[26:27]
	global_load_dwordx4 v[48:51], v1, s[26:27]
	global_load_dwordx4 v[52:55], v2, s[26:27]
	global_load_dwordx4 v[56:59], v3, s[26:27]
	global_load_dwordx4 v[60:63], v4, s[26:27]
	global_load_dwordx4 v[64:67], v5, s[26:27]
	global_load_dwordx4 v[68:71], v6, s[26:27]
	global_load_dwordx4 v[72:75], v7, s[26:27]
	global_load_dwordx4 v[76:79], v8, s[26:27]
	global_load_dwordx4 v[80:83], v9, s[26:27]
	global_load_dwordx4 v[84:87], v10, s[26:27]
	global_load_dwordx4 v[88:91], v11, s[26:27]
	global_load_dwordx4 v[92:95], v16, s[26:27]
	global_load_dwordx4 v[104:107], v17, s[26:27]
	global_load_dwordx4 v[108:111], v18, s[26:27]
	global_load_dwordx4 v[112:115], v19, s[26:27]
	s_mov_b64 exec, -1
	global_load_dwordx2 v[116:117], v30, s[28:29]
	global_load_dwordx2 v[118:119], v30, s[28:29] offset:32
	global_load_dwordx2 v[120:121], v30, s[28:29] offset:64
	global_load_dwordx2 v[122:123], v30, s[28:29] offset:96
	global_load_dwordx2 v[124:125], v30, s[28:29] offset:128
	global_load_dwordx2 v[126:127], v30, s[28:29] offset:160
	global_load_dwordx2 v[128:129], v30, s[28:29] offset:192
	global_load_dwordx2 v[130:131], v30, s[28:29] offset:224
	s_waitcnt vmcnt(0)
	s_branch .Ltrn_body
.Ltrn_loop:
	s_waitcnt vmcnt(4)
.Ltrn_body:
	s_mul_i32 s23, s8, 0x8fb9
	s_lshr_b32 s23, s23, 22
	s_mul_i32 s25, s23, 0x72
	s_sub_i32 s24, s8, s25
	s_lshl_b32 s33, s24, 19
	s_lshl_b32 s25, s23, 7
	s_add_i32 s33, s33, s25
	s_add_u32 s30, s6, s33
	s_addc_u32 s31, s7, 0
	s_mov_b32 s5, s24
	v_mul_f32_e32 v34, v44, v116
	v_mul_f32_e32 v35, v48, v117
	v_cvt_pk_bf16_f32 v38, v34, v35
	ds_write_b32 v28, v38
	v_mul_f32_e32 v36, v45, v116
	v_mul_f32_e32 v37, v49, v117
	v_cvt_pk_bf16_f32 v39, v36, v37
	ds_write_b32 v28, v39 offset:4
	v_mul_f32_e32 v34, v46, v116
	v_mul_f32_e32 v35, v50, v117
	v_cvt_pk_bf16_f32 v40, v34, v35
	ds_write_b32 v28, v40 offset:8
	v_mul_f32_e32 v36, v47, v116
	v_mul_f32_e32 v37, v51, v117
	v_cvt_pk_bf16_f32 v41, v36, v37
	ds_write_b32 v28, v41 offset:12
	v_mul_f32_e32 v34, v52, v118
	v_mul_f32_e32 v35, v56, v119
	v_cvt_pk_bf16_f32 v38, v34, v35
	ds_write_b32 v28, v38 offset:1040
	v_mul_f32_e32 v36, v53, v118
	v_mul_f32_e32 v37, v57, v119
	v_cvt_pk_bf16_f32 v39, v36, v37
	ds_write_b32 v28, v39 offset:1044
	v_mul_f32_e32 v34, v54, v118
	v_mul_f32_e32 v35, v58, v119
	v_cvt_pk_bf16_f32 v40, v34, v35
	ds_write_b32 v28, v40 offset:1048
	v_mul_f32_e32 v36, v55, v118
	v_mul_f32_e32 v37, v59, v119
	v_cvt_pk_bf16_f32 v41, v36, v37
	ds_write_b32 v28, v41 offset:1052
	v_mul_f32_e32 v34, v60, v120
	v_mul_f32_e32 v35, v64, v121
	v_cvt_pk_bf16_f32 v38, v34, v35
	ds_write_b32 v28, v38 offset:2080
	v_mul_f32_e32 v36, v61, v120
	v_mul_f32_e32 v37, v65, v121
	v_cvt_pk_bf16_f32 v39, v36, v37
	ds_write_b32 v28, v39 offset:2084
	v_mul_f32_e32 v34, v62, v120
	v_mul_f32_e32 v35, v66, v121
	v_cvt_pk_bf16_f32 v40, v34, v35
	ds_write_b32 v28, v40 offset:2088
	v_mul_f32_e32 v36, v63, v120
	v_mul_f32_e32 v37, v67, v121
	v_cvt_pk_bf16_f32 v41, v36, v37
	ds_write_b32 v28, v41 offset:2092
	v_mul_f32_e32 v34, v68, v122
	v_mul_f32_e32 v35, v72, v123
	v_cvt_pk_bf16_f32 v38, v34, v35
	ds_write_b32 v28, v38 offset:3120
	v_mul_f32_e32 v36, v69, v122
	v_mul_f32_e32 v37, v73, v123
	v_cvt_pk_bf16_f32 v39, v36, v37
	ds_write_b32 v28, v39 offset:3124
	v_mul_f32_e32 v34, v70, v122
	v_mul_f32_e32 v35, v74, v123
	v_cvt_pk_bf16_f32 v40, v34, v35
	ds_write_b32 v28, v40 offset:3128
	v_mul_f32_e32 v36, v71, v122
	v_mul_f32_e32 v37, v75, v123
	v_cvt_pk_bf16_f32 v41, v36, v37
	ds_write_b32 v28, v41 offset:3132
	v_mul_f32_e32 v34, v76, v124
	v_mul_f32_e32 v35, v80, v125
	v_cvt_pk_bf16_f32 v38, v34, v35
	ds_write_b32 v28, v38 offset:4160
	v_mul_f32_e32 v36, v77, v124
	v_mul_f32_e32 v37, v81, v125
	v_cvt_pk_bf16_f32 v39, v36, v37
	ds_write_b32 v28, v39 offset:4164
	v_mul_f32_e32 v34, v78, v124
	v_mul_f32_e32 v35, v82, v125
	v_cvt_pk_bf16_f32 v40, v34, v35
	ds_write_b32 v28, v40 offset:4168
	v_mul_f32_e32 v36, v79, v124
	v_mul_f32_e32 v37, v83, v125
	v_cvt_pk_bf16_f32 v41, v36, v37
	ds_write_b32 v28, v41 offset:4172
	v_mul_f32_e32 v34, v84, v126
	v_mul_f32_e32 v35, v88, v127
	v_cvt_pk_bf16_f32 v38, v34, v35
	ds_write_b32 v28, v38 offset:5200
	v_mul_f32_e32 v36, v85, v126
	v_mul_f32_e32 v37, v89, v127
	v_cvt_pk_bf16_f32 v39, v36, v37
	ds_write_b32 v28, v39 offset:5204
	v_mul_f32_e32 v34, v86, v126
	v_mul_f32_e32 v35, v90, v127
	v_cvt_pk_bf16_f32 v40, v34, v35
	ds_write_b32 v28, v40 offset:5208
	v_mul_f32_e32 v36, v87, v126
	v_mul_f32_e32 v37, v91, v127
	v_cvt_pk_bf16_f32 v41, v36, v37
	ds_write_b32 v28, v41 offset:5212
	v_mul_f32_e32 v34, v92, v128
	v_mul_f32_e32 v35, v104, v129
	v_cvt_pk_bf16_f32 v38, v34, v35
	ds_write_b32 v28, v38 offset:6240
	v_mul_f32_e32 v36, v93, v128
	v_mul_f32_e32 v37, v105, v129
	v_cvt_pk_bf16_f32 v39, v36, v37
	ds_write_b32 v28, v39 offset:6244
	v_mul_f32_e32 v34, v94, v128
	v_mul_f32_e32 v35, v106, v129
	v_cvt_pk_bf16_f32 v40, v34, v35
	ds_write_b32 v28, v40 offset:6248
	v_mul_f32_e32 v36, v95, v128
	v_mul_f32_e32 v37, v107, v129
	v_cvt_pk_bf16_f32 v41, v36, v37
	ds_write_b32 v28, v41 offset:6252
	v_mul_f32_e32 v34, v108, v130
	v_mul_f32_e32 v35, v112, v131
	v_cvt_pk_bf16_f32 v38, v34, v35
	ds_write_b32 v28, v38 offset:7280
	v_mul_f32_e32 v36, v109, v130
	v_mul_f32_e32 v37, v113, v131
	v_cvt_pk_bf16_f32 v39, v36, v37
	ds_write_b32 v28, v39 offset:7284
	v_mul_f32_e32 v34, v110, v130
	v_mul_f32_e32 v35, v114, v131
	v_cvt_pk_bf16_f32 v40, v34, v35
	ds_write_b32 v28, v40 offset:7288
	v_mul_f32_e32 v36, v111, v130
	v_mul_f32_e32 v37, v115, v131
	v_cvt_pk_bf16_f32 v41, v36, v37
	ds_write_b32 v28, v41 offset:7292
	s_add_i32 s9, s8, 0x400
	s_cmpk_lt_i32 s9, 0x1c80
	s_cbranch_scc0 .Ltrn_noload
	s_mul_i32 s23, s9, 0x8fb9
	s_lshr_b32 s23, s23, 22
	s_mul_i32 s25, s23, 0x72
	s_sub_i32 s24, s9, s25
	s_mul_i32 s25, s23, 0x1c6000
	s_lshl_b32 s33, s24, 8
	s_add_i32 s25, s25, s33
	s_add_u32 s26, s34, s25
	s_addc_u32 s27, s35, 0
	s_lshl_b32 s25, s23, 8
	s_add_u32 s28, s36, s25
	s_addc_u32 s29, s37, 0
	s_cmpk_lg_u32 s24, 0x71
	s_cbranch_scc1 .Ltrn_ldfull2
	s_mov_b32 exec_lo, 0x00ff00ff
	s_mov_b32 exec_hi, 0x00ff00ff
.Ltrn_ldfull2:
	global_load_dwordx4 v[44:47], v0, s[26:27]
	global_load_dwordx4 v[48:51], v1, s[26:27]
	global_load_dwordx4 v[52:55], v2, s[26:27]
	global_load_dwordx4 v[56:59], v3, s[26:27]
	global_load_dwordx4 v[60:63], v4, s[26:27]
	global_load_dwordx4 v[64:67], v5, s[26:27]
	global_load_dwordx4 v[68:71], v6, s[26:27]
	global_load_dwordx4 v[72:75], v7, s[26:27]
	global_load_dwordx4 v[76:79], v8, s[26:27]
	global_load_dwordx4 v[80:83], v9, s[26:27]
	global_load_dwordx4 v[84:87], v10, s[26:27]
	global_load_dwordx4 v[88:91], v11, s[26:27]
	global_load_dwordx4 v[92:95], v16, s[26:27]
	global_load_dwordx4 v[104:107], v17, s[26:27]
	global_load_dwordx4 v[108:111], v18, s[26:27]
	global_load_dwordx4 v[112:115], v19, s[26:27]
	s_mov_b64 exec, -1
	global_load_dwordx2 v[116:117], v30, s[28:29]
	global_load_dwordx2 v[118:119], v30, s[28:29] offset:32
	global_load_dwordx2 v[120:121], v30, s[28:29] offset:64
	global_load_dwordx2 v[122:123], v30, s[28:29] offset:96
	global_load_dwordx2 v[124:125], v30, s[28:29] offset:128
	global_load_dwordx2 v[126:127], v30, s[28:29] offset:160
	global_load_dwordx2 v[128:129], v30, s[28:29] offset:192
	global_load_dwordx2 v[130:131], v30, s[28:29] offset:224
.Ltrn_noload:
	s_waitcnt lgkmcnt(0)
	ds_read2_b32 v[180:181], v29 offset0:0 offset1:65
	ds_read2_b32 v[182:183], v29 offset0:130 offset1:195
	ds_read2_b32 v[188:189], v29 offset0:8 offset1:73
	ds_read2_b32 v[190:191], v29 offset0:138 offset1:203
	ds_read2_b32 v[196:197], v29 offset0:16 offset1:81
	ds_read2_b32 v[198:199], v29 offset0:146 offset1:211
	ds_read2_b32 v[200:201], v29 offset0:24 offset1:89
	ds_read2_b32 v[202:203], v29 offset0:154 offset1:219
	ds_read2_b32 v[204:205], v29 offset0:32 offset1:97
	ds_read2_b32 v[206:207], v29 offset0:162 offset1:227
	ds_read2_b32 v[232:233], v29 offset0:40 offset1:105
	ds_read2_b32 v[234:235], v29 offset0:170 offset1:235
	ds_read2_b32 v[236:237], v29 offset0:48 offset1:113
	ds_read2_b32 v[238:239], v29 offset0:178 offset1:243
	ds_read2_b32 v[240:241], v29 offset0:56 offset1:121
	ds_read2_b32 v[242:243], v29 offset0:186 offset1:251
	s_waitcnt lgkmcnt(0)
	global_store_dwordx4 v20, v[180:183], s[30:31]
	global_store_dwordx4 v21, v[188:191], s[30:31]
	global_store_dwordx4 v22, v[196:199], s[30:31]
	global_store_dwordx4 v23, v[200:203], s[30:31]
	s_cmpk_eq_u32 s5, 0x71
	s_cbranch_scc1 .Ltrn_st4
	global_store_dwordx4 v24, v[204:207], s[30:31]
	global_store_dwordx4 v25, v[232:235], s[30:31]
	global_store_dwordx4 v26, v[236:239], s[30:31]
	global_store_dwordx4 v27, v[240:243], s[30:31]
.Ltrn_st4:
	s_mov_b32 s8, s9
	s_cmpk_lt_i32 s8, 0x1c80
	s_cbranch_scc1 .Ltrn_loop
.Ltrn_done:
.LBB0_2224:
	v_readlane_b32 s4, v254, 40
	s_add_i32 s22, s4, 13
	s_cmp_ge_i32 s22, s65
	s_cbranch_scc1 .LBB0_2273
	s_waitcnt vmcnt(0)
	s_waitcnt vmcnt(0) lgkmcnt(0)
	s_barrier
	s_mov_b64 s[4:5], exec
	v_readlane_b32 s6, v253, 27
	v_readlane_b32 s7, v253, 28
	s_and_b64 s[6:7], s[4:5], s[6:7]
	s_mov_b64 exec, s[6:7]
	s_cbranch_execz .LBB0_2272
	v_mov_b32_e32 v0, s79
	s_waitcnt vmcnt(0) expcnt(0) lgkmcnt(0)
	ds_read_b32 v2, v0
	ds_read_b32 v0, v0 offset:4
	s_waitcnt lgkmcnt(1)
	v_cmp_ne_u32_e32 vcc, 0, v2
	s_cbranch_vccnz .LBB0_2240
	v_readlane_b32 s8, v251, 0
	v_readlane_b32 s9, v251, 1
	s_load_dwordx2 s[6:7], s[8:9], 0x4
	s_mov_b32 s14, 0
	s_waitcnt lgkmcnt(0)
	s_mul_i32 s13, s6, s97
	s_mul_i32 s13, s13, s7
	s_branch .LBB0_2229
